# attention: queue head fetched one item ahead, rel-pos-bias load not waited before K/V loads, loop-top vmcnt(4)
# speedup vs baseline: 1.0276x; 1.0075x over previous
; #define LAS __attribute__((address_space(3)))
; __device__ __forceinline__ void attn_phase(const Params& p, LAS unsigned char* lds) {
;     const int tid = threadIdx.x, lane = tid & 63, w = __builtin_amdgcn_readfirstlane(tid >> 6), fr = lane & 15, fq = lane >> 4;
;     LAS unsigned char* Ks = lds;
;     LAS unsigned char* Vs = lds + 73728;
;     LAS float* rp = (LAS float*)(lds + 147456);
;     volatile LAS unsigned* slot = (volatile LAS unsigned*)(lds + 147456 + 2048);
;     const bf16_t* QH = (const bf16_t*)(p.ws + WS_QK); const bf16_t* KH = (const bf16_t*)(p.ws + WS_QK + (16u << 20)); const bf16_t* VTA = (const bf16_t*)(p.ws + WS_VTA);
;     bf16_t* YCAT = (bf16_t*)(p.ws + WS_YCAT); float* SSQNA = (float*)(p.ws + WS_SSQ1 + 512 * 1024);
;     const float sc2 = 0.125f * 1.4426950408889634f;
;     unsigned* ctr = (unsigned*)(p.ws + WS_BAR) + 3584;
;     const int ri = w >> 2, qb = w & 3, q0 = qb * 16, kc0 = min(max(q0 - 8, 0), 32);
;     const int kperm = 8 * (fr >> 2) + (fr & 3);
;     for (;;) {
;         __syncthreads();
;         if (tid == 0) slot[0] = __hip_atomic_fetch_add(ctr, 1u, __ATOMIC_RELAXED, __HIP_MEMORY_SCOPE_AGENT);
.LBB0_335:
	s_waitcnt lgkmcnt(0)
	s_add_u32 s12, s34, 0x180000
	s_addc_u32 s13, s35, 0
	v_readfirstlane_b32 s0, v170
	s_add_u32 s14, s34, 0x83800
	s_addc_u32 s15, s35, 0
	s_lshr_b32 s10, s0, 8
	s_lshr_b32 s0, s0, 2
	s_and_b32 s0, s0, 48
	v_sub_u32_e64 v0, s0, 8 clamp
	v_min_u32_e32 v4, 32, v0
	v_lshlrev_b32_e32 v0, 1, v170
	v_and_b32_e32 v1, 3, v170
	v_mov_b32_e32 v31, 0
	v_lshlrev_b32_e32 v30, 1, v130
	v_and_or_b32 v5, v0, 24, v1
	v_or_b32_e32 v28, s0, v131
	v_lshl_add_u64 v[0:1], s[34:35], 0, v[30:31]
	s_mov_b64 s[0:1], 0x5f00000
	v_lshl_add_u64 v[32:33], v[0:1], 0, s[0:1]
	v_and_b32_e32 v1, 7, v170
	v_bfe_u32 v2, v170, 4, 1
	v_and_b32_e32 v3, 6, v133
	v_bitop3_b32 v2, v2, v1, v3 bitop3:0x36
	v_lshlrev_b32_e32 v6, 4, v2
	v_xor_b32_e32 v2, v172, v170
	v_lshlrev_b32_e32 v2, 4, v2
	v_lshlrev_b32_e32 v30, 4, v1
	v_lshlrev_b32_e32 v0, 7, v128
	v_and_b32_e32 v7, 0x70, v2
	v_lshl_add_u64 v[2:3], s[34:35], 0, v[30:31]
	s_mov_b64 s[4:5], 0x6f00000
	v_mov_b32_e32 v1, v31
	v_lshl_add_u64 v[34:35], v[2:3], 0, s[4:5]
	v_lshl_add_u64 v[2:3], s[34:35], 0, v[0:1]
	v_lshl_add_u64 v[2:3], v[2:3], 0, v[30:31]
	s_mov_b64 s[4:5], 0x7f00000
	v_add_u32_e32 v1, v4, v5
	v_lshl_add_u64 v[36:37], v[2:3], 0, s[4:5]
	v_lshrrev_b32_e32 v3, 2, v1
	v_bfe_u32 v2, v170, 1, 1
	v_and_b32_e32 v3, 6, v3
	v_bitop3_b32 v5, v3, v129, v2 bitop3:0x36
	v_lshlrev_b32_e32 v39, 4, v5
	v_or_b32_e32 v5, 4, v129
	s_add_i32 s4, 0, 0x12000
	v_bitop3_b32 v2, v3, v5, v2 bitop3:0x36
	v_add_u32_e32 v3, v4, v130
	v_lshrrev_b32_e32 v4, 3, v4
	v_add3_u32 v29, 0, v0, v6
	v_add3_u32 v38, s4, v0, v7
	v_lshrrev_b32_e32 v0, 1, v170
	v_lshlrev_b32_e32 v40, 4, v2
	v_sub_u32_e64 v2, v28, 8 clamp
	v_add_u32_e32 v4, v4, v129
	v_min_u32_e32 v2, 48, v2
	v_bitop3_b32 v0, v4, v0, 7 bitop3:0x78
	v_add_u32_e32 v5, 16, v2
	v_lshlrev_b32_e32 v6, 7, v131
	v_lshlrev_b32_e32 v0, 4, v0
	s_add_i32 s6, 0, 0x24000
	v_add3_u32 v41, s4, v6, v0
	v_lshl_add_u32 v42, v170, 2, s6
	v_cmp_ge_u32_e32 vcc, v3, v2
	v_cmp_lt_u32_e64 s[6:7], v3, v5
	v_sub_u32_e32 v6, v3, v28
	v_mov_b32_e32 v4, 0xf149f2ca
	s_and_b64 s[6:7], vcc, s[6:7]
	v_med3_i32 v46, v6, -15, 15
	v_or_b32_e32 v6, 1, v3
	v_cndmask_b32_e64 v45, v4, 0, s[6:7]
	v_cmp_ge_u32_e32 vcc, v6, v2
	v_cmp_lt_u32_e64 s[6:7], v6, v5
	v_sub_u32_e32 v6, v6, v28
	s_and_b64 s[6:7], vcc, s[6:7]
	v_med3_i32 v48, v6, -15, 15
	v_or_b32_e32 v6, 2, v3
	v_cndmask_b32_e64 v47, v4, 0, s[6:7]
	v_cmp_ge_u32_e32 vcc, v6, v2
	v_cmp_lt_u32_e64 s[6:7], v6, v5
	v_sub_u32_e32 v6, v6, v28
	s_and_b64 s[6:7], vcc, s[6:7]
	v_med3_i32 v50, v6, -15, 15
	v_or_b32_e32 v6, 3, v3
	v_cndmask_b32_e64 v49, v4, 0, s[6:7]
	v_cmp_ge_u32_e32 vcc, v6, v2
	v_cmp_lt_u32_e64 s[6:7], v6, v5
	v_sub_u32_e32 v6, v6, v28
	s_and_b64 s[6:7], vcc, s[6:7]
	v_med3_i32 v52, v6, -15, 15
	v_or_b32_e32 v6, 4, v3
	v_cndmask_b32_e64 v51, v4, 0, s[6:7]
	v_cmp_ge_u32_e32 vcc, v6, v2
	v_cmp_lt_u32_e64 s[6:7], v6, v5
	v_sub_u32_e32 v6, v6, v28
	s_and_b64 s[6:7], vcc, s[6:7]
	v_med3_i32 v54, v6, -15, 15
	v_or_b32_e32 v6, 5, v3
	v_cndmask_b32_e64 v53, v4, 0, s[6:7]
	v_cmp_ge_u32_e32 vcc, v6, v2
	v_cmp_lt_u32_e64 s[6:7], v6, v5
	v_sub_u32_e32 v6, v6, v28
	s_and_b64 s[6:7], vcc, s[6:7]
	v_med3_i32 v56, v6, -15, 15
	v_or_b32_e32 v6, 6, v3
	v_cndmask_b32_e64 v55, v4, 0, s[6:7]
	v_cmp_ge_u32_e32 vcc, v6, v2
	v_cmp_lt_u32_e64 s[6:7], v6, v5
	s_and_b64 s[6:7], vcc, s[6:7]
	v_or_b32_e32 v3, 7, v3
	v_lshlrev_b32_e32 v0, 2, v129
	v_cndmask_b32_e64 v57, v4, 0, s[6:7]
	v_cmp_ge_u32_e32 vcc, v3, v2
	v_cmp_lt_u32_e64 s[6:7], v3, v5
	s_movk_i32 s0, 0x1d1
	v_sub_u32_e32 v6, v6, v28
	s_and_b64 s[6:7], vcc, s[6:7]
	v_sub_u32_e32 v2, v3, v28
	v_lshlrev_b32_e32 v30, 1, v0
	v_mbcnt_lo_u32_b32 v0, -1, 0
	v_cmp_gt_u32_e64 s[0:1], s0, v170
	s_mov_b32 s17, 0
	v_cmp_eq_u32_e64 s[4:5], 0, v129
	v_add_u32_e32 v43, 0x10000, v29
	v_add_u32_e32 v44, 0x10000, v38
	s_mov_b32 s11, 0xf149f2ca
	v_med3_i32 v58, v6, -15, 15
	v_cndmask_b32_e64 v59, v4, 0, s[6:7]
	v_med3_i32 v60, v2, -15, 15
	v_lshl_add_u32 v61, v1, 7, 0
	s_add_i32 s33, 0, 0x24800
	s_movk_i32 s40, 0x3ff
	s_mov_b64 s[6:7], 0xb200400
	s_mov_b32 s41, 0xb200000
	v_mbcnt_hi_u32_b32 v62, -1, v0
	s_and_saveexec_b64 s[98:99], s[58:59]
	s_cbranch_execz .Lattn_pf_a
	v_mov_b32_e32 v243, 1
	global_atomic_add v242, v31, v243, s[14:15] sc0
.Lattn_pf_a:
	s_or_b64 exec, exec, s[98:99]
	s_waitcnt vmcnt(0)
	s_branch .LBB0_338

; #define LAS __attribute__((address_space(3)))
; __device__ __forceinline__ void attn_phase(const Params& p, LAS unsigned char* lds) {
;     ...
;         __syncthreads();
;         if (tid == 0) slot[0] = __hip_atomic_fetch_add(ctr, 1u, __ATOMIC_RELAXED, __HIP_MEMORY_SCOPE_AGENT);
;         __syncthreads();
;         const int item = (int)slot[0];
;         if (item >= 1024) break;
;         const int b = item >> 7, h = (item >> 4) & 7, r0 = (item & 15) * 2, R0 = min(max(r0 - 4, 0), 24);
;         const int r = r0 + ri, rs = min(max(r - 4, 0), 24), j0 = rs - R0;
;         const int tq = b * SEQ + r * 64 + q0 + fr;
;         const bf16_t* qp = QH + ((size_t)(b * 8 + h) * SEQ + r * 64 + q0 + fr) * 64 + fq * 8;
;         const bf16x8 qf0 = *(const bf16x8*)qp, qf1 = *(const bf16x8*)(qp + 32);
;         for (int u = tid; u < 465; u += NTHREADS) rp[u] = p.rpb[h * 465 + u] * 1.4426950408889634f;
;         { const int t = tid >> 3, c = tid & 7; const unsigned dstk = (unsigned)(t * 128 + ((c ^ (((t >> 1) & 1) | (((t >> 3) & 3) << 1))) << 4)), dstv = (unsigned)(t * 128 + ((c ^ ((t >> 1) & 7)) << 4));
;           u32x4 kv[9], vv[9];
; #pragma unroll
;           for (int j = 0; j < 9; ++j) { const int srow = min(R0 + j, 31);
;               kv[j] = *(const u32x4*)(KH + ((size_t)(b * 8 + h) * SEQ + srow * 64 + t) * 64 + c * 8);
;               vv[j] = *(const u32x4*)(VTA + ((size_t)((b * 8 + h) * 32 + srow) * 64 + t) * 64 + c * 8); }
; #pragma unroll
;           for (int j = 0; j < 9; ++j) { *(LAS u32x4*)(Ks + j * 8192 + dstk) = kv[j]; *(LAS u32x4*)(Vs + j * 8192 + dstv) = vv[j]; } }
.LBB0_338:
	s_waitcnt vmcnt(4)
	s_barrier
	s_and_saveexec_b64 s[20:21], s[58:59]
	s_cbranch_execz .LBB0_342
	v_mov_b32_e32 v1, s33
	ds_write_b32 v1, v242
.LBB0_342:
	s_or_b64 exec, exec, s[20:21]
	v_mov_b32_e32 v0, s33
	s_waitcnt lgkmcnt(0)
	s_barrier
	ds_read_b32 v0, v0
	s_mov_b64 s[20:21], -1
	s_waitcnt lgkmcnt(0)
	v_cmp_lt_i32_e32 vcc, s40, v0
	v_readfirstlane_b32 s16, v0
	s_cbranch_vccnz .LBB0_337
	s_ashr_i32 s43, s16, 7
	s_bfe_u32 s42, s16, 0x30004
	s_lshl_b32 s16, s16, 1
	s_lshl_b32 s20, s43, 3
	s_and_b32 s16, s16, 30
	s_or_b32 s20, s20, s42
	s_add_i32 s45, s16, s10
	s_ashr_i32 s21, s20, 31
	s_lshl_b32 s44, s45, 6
	s_lshl_b64 s[26:27], s[20:21], 11
	s_add_u32 s21, s26, s44
	s_addc_u32 s38, s27, 0
	v_mov_b32_e32 v1, s38
	v_or_b32_e32 v0, s21, v28
	v_lshlrev_b64 v[0:1], 7, v[0:1]
	v_lshl_add_u64 v[0:1], v[32:33], 0, v[0:1]
	global_load_dwordx4 v[12:15], v[0:1], off
	global_load_dwordx4 v[4:7], v[0:1], off offset:64
	s_and_saveexec_b64 s[38:39], s[0:1]
	s_cbranch_execz .LBB0_345
	s_mul_i32 s21, s42, 0x1d1
	v_add_lshl_u32 v0, s21, v170, 2
	global_load_dword v241, v0, s[50:51]
.LBB0_345:
	s_or_b64 exec, exec, s[38:39]
	v_sub_u32_e64 v0, s16, 4 clamp
	v_or_b32_e32 v108, s26, v128
	v_readfirstlane_b32 s38, v0
	s_min_u32 s39, s38, 24
	s_lshl_b32 s26, s20, 5
	s_or_b32 s20, s39, s26
	s_ashr_i32 s21, s20, 31
	s_lshl_b64 s[20:21], s[20:21], 13
	v_lshl_add_u64 v[8:9], v[36:37], 0, s[20:21]
	s_or_b32 s20, s39, 1
	s_lshl_b32 s16, s20, 6
	s_or_b32 s20, s20, s26
	s_ashr_i32 s21, s20, 31
	s_lshl_b64 s[20:21], s[20:21], 13
	v_mov_b32_e32 v109, s27
	v_lshl_add_u64 v[20:21], v[36:37], 0, s[20:21]
	s_add_i32 s20, s39, 2
	v_lshl_add_u64 v[16:17], v[108:109], 0, s[16:17]
	s_lshl_b32 s16, s20, 6
	s_or_b32 s20, s20, s26
	s_ashr_i32 s21, s20, 31
	s_lshl_b64 s[20:21], s[20:21], 13
	v_lshl_add_u64 v[64:65], v[36:37], 0, s[20:21]
	s_add_i32 s20, s39, 3
	v_lshl_add_u64 v[24:25], v[108:109], 0, s[16:17]
	s_lshl_b32 s16, s20, 6
	s_or_b32 s20, s20, s26
	s_ashr_i32 s21, s20, 31
	s_lshl_b64 s[20:21], s[20:21], 13
	v_lshl_add_u64 v[72:73], v[36:37], 0, s[20:21]
	s_add_i32 s20, s39, 4
	v_lshl_add_u64 v[68:69], v[108:109], 0, s[16:17]
	s_lshl_b32 s16, s20, 6
	s_or_b32 s20, s20, s26
	s_ashr_i32 s21, s20, 31
	s_lshl_b64 s[20:21], s[20:21], 13
	v_lshl_add_u64 v[80:81], v[36:37], 0, s[20:21]
	s_add_i32 s20, s39, 5
	v_lshl_add_u64 v[76:77], v[108:109], 0, s[16:17]
	s_lshl_b32 s16, s20, 6
	s_or_b32 s20, s20, s26
	s_ashr_i32 s21, s20, 31
	s_lshl_b64 s[20:21], s[20:21], 13
	v_lshl_add_u64 v[88:89], v[36:37], 0, s[20:21]
	s_add_i32 s20, s39, 6
	v_lshl_add_u64 v[84:85], v[108:109], 0, s[16:17]
	s_lshl_b32 s16, s20, 6
	s_or_b32 s20, s20, s26
	s_ashr_i32 s21, s20, 31
	s_lshl_b64 s[20:21], s[20:21], 13
	v_lshl_add_u64 v[96:97], v[36:37], 0, s[20:21]
	s_add_i32 s20, s39, 7
	v_lshl_add_u64 v[92:93], v[108:109], 0, s[16:17]
	s_lshl_b32 s16, s20, 6
	s_or_b32 s20, s20, s26
	s_ashr_i32 s21, s20, 31
	v_lshl_add_u64 v[100:101], v[108:109], 0, s[16:17]
	s_lshl_b64 s[20:21], s[20:21], 13
	s_min_u32 s16, s38, 23
	v_lshl_add_u64 v[104:105], v[36:37], 0, s[20:21]
	s_add_i32 s20, s16, 8
	s_lshl_b32 s16, s20, 6
	s_or_b32 s20, s20, s26
	v_lshl_or_b32 v0, s39, 6, v108
	v_mov_b32_e32 v1, s27
	v_lshl_add_u64 v[108:109], v[108:109], 0, s[16:17]
	s_ashr_i32 s21, s20, 31
	v_lshlrev_b64 v[0:1], 7, v[0:1]
	v_lshlrev_b64 v[16:17], 7, v[16:17]
	v_lshlrev_b64 v[24:25], 7, v[24:25]
	v_lshlrev_b64 v[68:69], 7, v[68:69]
	v_lshlrev_b64 v[76:77], 7, v[76:77]
	v_lshlrev_b64 v[84:85], 7, v[84:85]
	v_lshlrev_b64 v[92:93], 7, v[92:93]
	v_lshlrev_b64 v[100:101], 7, v[100:101]
	v_lshlrev_b64 v[108:109], 7, v[108:109]
	s_lshl_b64 s[20:21], s[20:21], 13
	v_lshl_add_u64 v[0:1], v[34:35], 0, v[0:1]
	v_lshl_add_u64 v[16:17], v[34:35], 0, v[16:17]
	v_lshl_add_u64 v[24:25], v[34:35], 0, v[24:25]
	v_lshl_add_u64 v[68:69], v[34:35], 0, v[68:69]
	v_lshl_add_u64 v[76:77], v[34:35], 0, v[76:77]
	v_lshl_add_u64 v[84:85], v[34:35], 0, v[84:85]
	v_lshl_add_u64 v[92:93], v[34:35], 0, v[92:93]
	v_lshl_add_u64 v[100:101], v[34:35], 0, v[100:101]
	v_lshl_add_u64 v[108:109], v[34:35], 0, v[108:109]
	v_lshl_add_u64 v[112:113], v[36:37], 0, s[20:21]
	global_load_dwordx4 v[0:3], v[0:1], off
	s_nop 0
	global_load_dwordx4 v[8:11], v[8:9], off
	s_nop 0
	global_load_dwordx4 v[16:19], v[16:17], off
	s_nop 0
	global_load_dwordx4 v[20:23], v[20:21], off
	s_nop 0
	global_load_dwordx4 v[24:27], v[24:25], off
	s_nop 0
	global_load_dwordx4 v[64:67], v[64:65], off
	s_nop 0
	global_load_dwordx4 v[68:71], v[68:69], off
	s_nop 0
	global_load_dwordx4 v[72:75], v[72:73], off
	s_nop 0
	global_load_dwordx4 v[76:79], v[76:77], off
	s_nop 0
	global_load_dwordx4 v[80:83], v[80:81], off
	s_nop 0
	global_load_dwordx4 v[84:87], v[84:85], off
	s_nop 0
	global_load_dwordx4 v[88:91], v[88:89], off
	s_nop 0
	global_load_dwordx4 v[92:95], v[92:93], off
	s_nop 0
	global_load_dwordx4 v[96:99], v[96:97], off
	s_nop 0
	global_load_dwordx4 v[100:103], v[100:101], off
	s_nop 0
	global_load_dwordx4 v[104:107], v[104:105], off
	s_nop 0
	global_load_dwordx4 v[108:111], v[108:109], off
	s_nop 0
	global_load_dwordx4 v[112:115], v[112:113], off
	s_max_i32 s16, s45, 4
	s_add_i32 s16, s16, -4
	s_min_u32 s20, s16, 24
	s_sub_i32 s16, s20, s39
	s_lshl_b32 s16, s16, 13
	s_sub_i32 s20, s20, s45
	s_mulk_i32 s20, 0x7c
	s_add_i32 s20, s20, 0
	s_add_i32 s20, s20, 0x24000
	v_lshl_add_u32 v118, v58, 2, s20
	v_lshl_add_u32 v119, v60, 2, s20
	s_waitcnt vmcnt(18)
	s_and_saveexec_b64 s[98:99], s[0:1]
	v_mul_f32_e32 v241, 0x3fb8aa3b, v241
	ds_write_b32 v42, v241
	s_or_b64 exec, exec, s[98:99]
	s_waitcnt vmcnt(17)
	ds_write_b128 v29, v[0:3]
	s_waitcnt vmcnt(16)
	ds_write_b128 v38, v[8:11]
	s_waitcnt vmcnt(15)
	ds_write_b128 v29, v[16:19] offset:8192
	s_waitcnt vmcnt(14)
	ds_write_b128 v38, v[20:23] offset:8192
	s_waitcnt vmcnt(13)
	ds_write_b128 v29, v[24:27] offset:16384
	s_waitcnt vmcnt(12)
	ds_write_b128 v38, v[64:67] offset:16384
	s_waitcnt vmcnt(11)
	ds_write_b128 v29, v[68:71] offset:24576
	s_waitcnt vmcnt(10)
	ds_write_b128 v38, v[72:75] offset:24576
	s_waitcnt vmcnt(9)
	ds_write_b128 v29, v[76:79] offset:32768
	s_waitcnt vmcnt(8)
	ds_write_b128 v38, v[80:83] offset:32768
	s_waitcnt vmcnt(7)
	ds_write_b128 v29, v[84:87] offset:40960
	s_waitcnt vmcnt(6)
	ds_write_b128 v38, v[88:91] offset:40960
	s_waitcnt vmcnt(5)
	ds_write_b128 v29, v[92:95] offset:49152
	s_waitcnt vmcnt(4)
	ds_write_b128 v38, v[96:99] offset:49152
	s_waitcnt vmcnt(3)
	ds_write_b128 v29, v[100:103] offset:57344
	s_waitcnt vmcnt(2)
	ds_write_b128 v38, v[104:107] offset:57344
	s_waitcnt vmcnt(1)
	ds_write_b128 v43, v[108:111]
	s_waitcnt vmcnt(0)
	ds_write_b128 v44, v[112:115]
	v_add_u32_e32 v8, s16, v61
	v_add_u32_e32 v63, v8, v39
	s_waitcnt lgkmcnt(0)
	s_barrier
	s_and_saveexec_b64 s[98:99], s[58:59]
	s_cbranch_execz .Lattn_pf_b
	v_mov_b32_e32 v243, 1
	global_atomic_add v242, v31, v243, s[14:15] sc0
; #define LAS __attribute__((address_space(3)))
; __device__ __forceinline__ void attn_phase(const Params& p, LAS unsigned char* lds) {
;     ...
;         f32x4 s[8][2];
; #pragma unroll
;         for (int i = 0; i < 8; ++i)
; #pragma unroll
;             for (int t = 0; t < 2; ++t) { const int tok = kc0 + kperm + 4 * t; const LAS unsigned char* kr = Ks + (j0 + i) * 8192 + tok * 128;
;                 const int fk = ((tok >> 1) & 1) | (((tok >> 3) & 3) << 1);
;                 const bf16x8 k0 = *(const LAS bf16x8*)(kr + ((fq ^ fk) << 4)), k1 = *(const LAS bf16x8*)(kr + (((4 + fq) ^ fk) << 4));
;                 f32x4 a = (f32x4){0.f, 0.f, 0.f, 0.f};
;                 a = __builtin_amdgcn_mfma_f32_16x16x32_bf16(k0, qf0, a, 0, 0, 0); a = __builtin_amdgcn_mfma_f32_16x16x32_bf16(k1, qf1, a, 0, 0, 0); s[i][t] = a; }
;         const int qc = q0 + fr, cs0 = min(max(qc - 8, 0), 48);
;         float madd[2][4]; int dco[2][4];
; #pragma unroll
;         for (int t = 0; t < 2; ++t)
; #pragma unroll
;             for (int j = 0; j < 4; ++j) { const int kc = kc0 + 8 * fq + 4 * t + j; madd[t][j] = ((kc >= cs0) && (kc < cs0 + 16)) ? 0.f : -1e30f; dco[t][j] = min(max(kc - qc, -15), 15); }
;         float mx = -1e30f;
; #pragma unroll
;         for (int i = 0; i < 8; ++i) { const int dr = rs + i - r; const LAS float* rrow = rp + (dr + 7) * 31 + 15;
; #pragma unroll
;             for (int t = 0; t < 2; ++t)
; #pragma unroll
;                 for (int j = 0; j < 4; ++j) { const float v = (s[i][t][j] * sc2 + rrow[dco[t][j]]) + madd[t][j]; s[i][t][j] = v; mx = fmaxf(mx, v); } }
.Lattn_pf_b:
	s_or_b64 exec, exec, s[98:99]
	ds_read_b128 v[0:3], v63
	v_add_u32_e32 v112, v8, v40
	ds_read_b128 v[8:11], v63 offset:512
	s_waitcnt lgkmcnt(1)
	v_mfma_f32_16x16x32_bf16 v[0:3], v[0:3], v[12:15], 0
	ds_read_b128 v[16:19], v112
	ds_read_b128 v[20:23], v112 offset:512
	s_waitcnt lgkmcnt(1)
	v_mfma_f32_16x16x32_bf16 v[64:67], v[16:19], v[4:7], v[0:3]
	v_mfma_f32_16x16x32_bf16 v[0:3], v[8:11], v[12:15], 0
	s_waitcnt lgkmcnt(0)
	v_mfma_f32_16x16x32_bf16 v[68:71], v[20:23], v[4:7], v[0:3]
	s_nop 5
	ds_read_b128 v[0:3], v63 offset:8192
	ds_read_b128 v[8:11], v63 offset:8704
	ds_read_b128 v[16:19], v112 offset:8192
	ds_read_b128 v[20:23], v112 offset:8704
	s_waitcnt lgkmcnt(3)
	v_mfma_f32_16x16x32_bf16 v[0:3], v[0:3], v[12:15], 0
	s_waitcnt lgkmcnt(1)
	v_mfma_f32_16x16x32_bf16 v[72:75], v[16:19], v[4:7], v[0:3]
	v_mfma_f32_16x16x32_bf16 v[0:3], v[8:11], v[12:15], 0
	s_waitcnt lgkmcnt(0)
	v_mfma_f32_16x16x32_bf16 v[76:79], v[20:23], v[4:7], v[0:3]
	s_nop 5
	ds_read_b128 v[0:3], v63 offset:16384
	ds_read_b128 v[8:11], v63 offset:16896
	ds_read_b128 v[16:19], v112 offset:16384
	ds_read_b128 v[20:23], v112 offset:16896
	s_waitcnt lgkmcnt(3)
	v_mfma_f32_16x16x32_bf16 v[0:3], v[0:3], v[12:15], 0
	s_waitcnt lgkmcnt(1)
	v_mfma_f32_16x16x32_bf16 v[80:83], v[16:19], v[4:7], v[0:3]
	v_mfma_f32_16x16x32_bf16 v[0:3], v[8:11], v[12:15], 0
	s_waitcnt lgkmcnt(0)
	v_mfma_f32_16x16x32_bf16 v[84:87], v[20:23], v[4:7], v[0:3]
	s_nop 5
	ds_read_b128 v[0:3], v63 offset:24576
	ds_read_b128 v[8:11], v63 offset:25088
	ds_read_b128 v[16:19], v112 offset:24576
	ds_read_b128 v[20:23], v112 offset:25088
	s_waitcnt lgkmcnt(3)
	v_mfma_f32_16x16x32_bf16 v[0:3], v[0:3], v[12:15], 0
	s_waitcnt lgkmcnt(1)
	v_mfma_f32_16x16x32_bf16 v[88:91], v[16:19], v[4:7], v[0:3]
	v_mfma_f32_16x16x32_bf16 v[0:3], v[8:11], v[12:15], 0
	s_waitcnt lgkmcnt(0)
	v_mfma_f32_16x16x32_bf16 v[92:95], v[20:23], v[4:7], v[0:3]
	s_nop 5
	ds_read_b128 v[0:3], v63 offset:32768
	ds_read_b128 v[8:11], v63 offset:33280
	ds_read_b128 v[16:19], v112 offset:32768
	ds_read_b128 v[20:23], v112 offset:33280
	s_waitcnt lgkmcnt(3)
	v_mfma_f32_16x16x32_bf16 v[0:3], v[0:3], v[12:15], 0
	s_waitcnt lgkmcnt(1)
	v_mfma_f32_16x16x32_bf16 v[96:99], v[16:19], v[4:7], v[0:3]
	v_mfma_f32_16x16x32_bf16 v[0:3], v[8:11], v[12:15], 0
	s_waitcnt lgkmcnt(0)
	v_mfma_f32_16x16x32_bf16 v[100:103], v[20:23], v[4:7], v[0:3]
	s_nop 5
	ds_read_b128 v[0:3], v63 offset:40960
	ds_read_b128 v[8:11], v63 offset:41472
	ds_read_b128 v[16:19], v112 offset:40960
	ds_read_b128 v[20:23], v112 offset:41472
	s_waitcnt lgkmcnt(3)
	v_mfma_f32_16x16x32_bf16 v[0:3], v[0:3], v[12:15], 0
	s_waitcnt lgkmcnt(1)
	v_mfma_f32_16x16x32_bf16 v[24:27], v[16:19], v[4:7], v[0:3]
	v_mfma_f32_16x16x32_bf16 v[0:3], v[8:11], v[12:15], 0
	s_waitcnt lgkmcnt(0)
	v_mfma_f32_16x16x32_bf16 v[20:23], v[20:23], v[4:7], v[0:3]
	s_nop 5
	ds_read_b128 v[0:3], v63 offset:49152
	ds_read_b128 v[8:11], v63 offset:49664
	ds_read_b128 v[16:19], v112 offset:49152
	ds_read_b128 v[104:107], v112 offset:49664
	s_waitcnt lgkmcnt(3)
	v_mfma_f32_16x16x32_bf16 v[0:3], v[0:3], v[12:15], 0
	s_waitcnt lgkmcnt(1)
	v_mfma_f32_16x16x32_bf16 v[16:19], v[16:19], v[4:7], v[0:3]
	v_mfma_f32_16x16x32_bf16 v[0:3], v[8:11], v[12:15], 0
	s_waitcnt lgkmcnt(0)
	v_mfma_f32_16x16x32_bf16 v[8:11], v[104:107], v[4:7], v[0:3]
	s_nop 5
	ds_read_b128 v[0:3], v63 offset:57344
	ds_read_b128 v[104:107], v63 offset:57856
	ds_read_b128 v[108:111], v112 offset:57344
	ds_read_b128 v[112:115], v112 offset:57856
	v_lshl_add_u32 v63, v46, 2, s20
	s_waitcnt lgkmcnt(3)
	v_mfma_f32_16x16x32_bf16 v[0:3], v[0:3], v[12:15], 0
	s_waitcnt lgkmcnt(1)
	v_mfma_f32_16x16x32_bf16 v[0:3], v[108:111], v[4:7], v[0:3]
	v_lshl_add_u32 v110, v48, 2, s20
	v_lshl_add_u32 v111, v52, 2, s20
	v_mfma_f32_16x16x32_bf16 v[12:15], v[104:107], v[12:15], 0
	v_add_u32_e32 v104, 0x200, v63
	v_add_u32_e32 v106, 0x200, v110
	ds_read2_b32 v[104:105], v104 offset0:104 offset1:135
	ds_read2_b32 v[106:107], v106 offset0:104 offset1:135
	s_waitcnt lgkmcnt(2)
	v_mfma_f32_16x16x32_bf16 v[4:7], v[112:115], v[4:7], v[12:15]
	v_lshl_add_u32 v114, v54, 2, s20
	v_lshl_add_u32 v115, v56, 2, s20
	s_waitcnt lgkmcnt(1)
	v_fmac_f32_e32 v105, 0x3e38aa3b, v72
	v_fmamk_f32 v12, v64, 0x3e38aa3b, v104
	s_waitcnt lgkmcnt(0)
	v_fmamk_f32 v64, v65, 0x3e38aa3b, v106
	v_lshl_add_u32 v106, v50, 2, s20
	v_add_f32_e32 v104, v45, v12
	v_add_u32_e32 v12, 0x200, v106
	ds_read2_b32 v[12:13], v12 offset0:104 offset1:135
	v_add_u32_e32 v14, 0x200, v111
	ds_read2_b32 v[14:15], v14 offset0:104 offset1:135
	v_add_f32_e32 v112, v47, v64
	v_max3_f32 v108, v104, s11, v112
	s_waitcnt lgkmcnt(1)
	v_fmamk_f32 v12, v66, 0x3e38aa3b, v12
	v_add_f32_e32 v113, v49, v12
	s_waitcnt lgkmcnt(0)
	v_fmamk_f32 v12, v67, 0x3e38aa3b, v14
	v_add_u32_e32 v14, 0x200, v114
	ds_read2_b32 v[64:65], v14 offset0:104 offset1:135
	v_add_u32_e32 v14, 0x200, v115
	ds_read2_b32 v[66:67], v14 offset0:104 offset1:135
	v_add_f32_e32 v116, v51, v12
	v_max3_f32 v12, v108, v113, v116
	s_waitcnt lgkmcnt(1)
	v_fmamk_f32 v14, v68, 0x3e38aa3b, v64
	v_add_u32_e32 v64, 0x200, v118
	v_add_f32_e32 v117, v53, v14
	s_waitcnt lgkmcnt(0)
	v_fmamk_f32 v14, v69, 0x3e38aa3b, v66
	ds_read2_b32 v[68:69], v64 offset0:104 offset1:135
	v_add_u32_e32 v64, 0x200, v119
	ds_read2_b32 v[108:109], v64 offset0:104 offset1:135
	v_add_f32_e32 v120, v55, v14
	v_max3_f32 v12, v12, v117, v120
	s_waitcnt lgkmcnt(1)
	v_fmamk_f32 v14, v70, 0x3e38aa3b, v68
	v_add_f32_e32 v121, v57, v14
	s_waitcnt lgkmcnt(0)
; #define LAS __attribute__((address_space(3)))
; __device__ __forceinline__ void attn_phase(const Params& p, LAS unsigned char* lds) {
;     ...
;         float mx = -1e30f;
; #pragma unroll
;         for (int i = 0; i < 8; ++i) { const int dr = rs + i - r; const LAS float* rrow = rp + (dr + 7) * 31 + 15;
; #pragma unroll
;             for (int t = 0; t < 2; ++t)
; #pragma unroll
;                 for (int j = 0; j < 4; ++j) { const float v = (s[i][t][j] * sc2 + rrow[dco[t][j]]) + madd[t][j]; s[i][t][j] = v; mx = fmaxf(mx, v); } }
	v_fmamk_f32 v14, v71, 0x3e38aa3b, v108
	v_add_f32_e32 v108, v59, v14
	v_fmac_f32_e32 v107, 0x3e38aa3b, v73
	v_max3_f32 v12, v12, v121, v108
	v_add_f32_e32 v105, v45, v105
	v_add_f32_e32 v107, v47, v107
	v_fmac_f32_e32 v13, 0x3e38aa3b, v74
	v_fmac_f32_e32 v15, 0x3e38aa3b, v75
	v_max3_f32 v12, v12, v105, v107
	v_add_f32_e32 v122, v49, v13
	v_add_f32_e32 v123, v51, v15
	v_fmac_f32_e32 v65, 0x3e38aa3b, v76
	v_fmac_f32_e32 v67, 0x3e38aa3b, v77
	v_max3_f32 v12, v12, v122, v123
	v_add_f32_e32 v76, v53, v65
	v_add_f32_e32 v77, v55, v67
	v_add_u32_e32 v63, 0x400, v63
	v_max3_f32 v64, v12, v76, v77
	v_fmac_f32_e32 v109, 0x3e38aa3b, v79
	ds_read2_b32 v[12:13], v63 offset0:38 offset1:69
	v_add_u32_e32 v79, 0x400, v110
	ds_read2_b32 v[14:15], v79 offset0:38 offset1:69
	v_fmac_f32_e32 v69, 0x3e38aa3b, v78
	v_add_f32_e32 v78, v57, v69
	s_waitcnt lgkmcnt(1)
	v_fmamk_f32 v12, v80, 0x3e38aa3b, v12
	v_add_f32_e32 v109, v59, v109
	v_add_f32_e32 v80, v45, v12
	s_waitcnt lgkmcnt(0)
	v_fmamk_f32 v12, v81, 0x3e38aa3b, v14
	v_add_u32_e32 v81, 0x400, v106
	v_max3_f32 v68, v64, v78, v109
	ds_read2_b32 v[64:65], v81 offset0:38 offset1:69
	v_add_u32_e32 v106, 0x400, v111
	ds_read2_b32 v[66:67], v106 offset0:38 offset1:69
	v_add_f32_e32 v110, v47, v12
	v_max3_f32 v12, v68, v80, v110
	s_waitcnt lgkmcnt(1)
	v_fmamk_f32 v14, v82, 0x3e38aa3b, v64
	v_add_f32_e32 v82, v49, v14
	s_waitcnt lgkmcnt(0)
	v_fmamk_f32 v14, v83, 0x3e38aa3b, v66
	v_add_u32_e32 v83, 0x400, v114
	ds_read2_b32 v[68:69], v83 offset0:38 offset1:69
	v_add_u32_e32 v111, 0x400, v115
	ds_read2_b32 v[70:71], v111 offset0:38 offset1:69
	v_add_f32_e32 v114, v51, v14
	v_add_u32_e32 v115, 0x400, v119
	s_waitcnt lgkmcnt(1)
	v_fmamk_f32 v14, v84, 0x3e38aa3b, v68
	v_add_f32_e32 v84, v53, v14
	s_waitcnt lgkmcnt(0)
	v_fmamk_f32 v14, v85, 0x3e38aa3b, v70
	v_add_u32_e32 v85, 0x400, v118
	ds_read2_b32 v[72:73], v85 offset0:38 offset1:69
	ds_read2_b32 v[74:75], v115 offset0:38 offset1:69
	v_add_f32_e32 v118, v55, v14
	v_max3_f32 v12, v12, v82, v114
	v_max3_f32 v12, v12, v84, v118
	s_waitcnt lgkmcnt(1)
	v_fmamk_f32 v14, v86, 0x3e38aa3b, v72
	v_add_f32_e32 v86, v57, v14
	s_waitcnt lgkmcnt(0)
	v_fmamk_f32 v14, v87, 0x3e38aa3b, v74
	v_add_f32_e32 v87, v59, v14
	v_fmac_f32_e32 v13, 0x3e38aa3b, v88
	v_fmac_f32_e32 v15, 0x3e38aa3b, v89
	v_max3_f32 v12, v12, v86, v87
	v_add_f32_e32 v88, v45, v13
	v_add_f32_e32 v89, v47, v15
	v_fmac_f32_e32 v65, 0x3e38aa3b, v90
	v_fmac_f32_e32 v67, 0x3e38aa3b, v91
	v_max3_f32 v12, v12, v88, v89
	v_add_f32_e32 v90, v49, v65
	v_add_f32_e32 v91, v51, v67
	v_fmac_f32_e32 v69, 0x3e38aa3b, v92
	v_fmac_f32_e32 v71, 0x3e38aa3b, v93
	v_max3_f32 v12, v12, v90, v91
	v_add_f32_e32 v92, v53, v69
	v_add_f32_e32 v93, v55, v71
	v_max3_f32 v64, v12, v92, v93
	ds_read2_b32 v[12:13], v63 offset0:100 offset1:131
	ds_read2_b32 v[14:15], v79 offset0:100 offset1:131
	v_fmac_f32_e32 v73, 0x3e38aa3b, v94
	v_fmac_f32_e32 v75, 0x3e38aa3b, v95
	v_add_f32_e32 v94, v57, v73
	v_add_f32_e32 v95, v59, v75
	s_waitcnt lgkmcnt(1)
	v_fmamk_f32 v12, v96, 0x3e38aa3b, v12
	v_max3_f32 v68, v64, v94, v95
	v_add_f32_e32 v96, v45, v12
	ds_read2_b32 v[64:65], v81 offset0:100 offset1:131
	s_waitcnt lgkmcnt(1)
	v_fmamk_f32 v12, v97, 0x3e38aa3b, v14
	v_add_f32_e32 v97, v47, v12
	ds_read2_b32 v[66:67], v106 offset0:100 offset1:131
	v_max3_f32 v12, v68, v96, v97
	ds_read2_b32 v[68:69], v83 offset0:100 offset1:131
	ds_read2_b32 v[70:71], v111 offset0:100 offset1:131
	ds_read2_b32 v[72:73], v85 offset0:100 offset1:131
	s_waitcnt lgkmcnt(4)
	v_fmamk_f32 v14, v98, 0x3e38aa3b, v64
	ds_read2_b32 v[74:75], v115 offset0:100 offset1:131
	v_add_f32_e32 v64, v49, v14
	s_waitcnt lgkmcnt(4)
	v_fmamk_f32 v14, v99, 0x3e38aa3b, v66
	v_add_f32_e32 v66, v51, v14
	s_waitcnt lgkmcnt(3)
	v_fmamk_f32 v14, v100, 0x3e38aa3b, v68
	v_add_f32_e32 v68, v53, v14
	s_waitcnt lgkmcnt(2)
	v_fmamk_f32 v14, v101, 0x3e38aa3b, v70
	v_add_f32_e32 v70, v55, v14
	s_waitcnt lgkmcnt(1)
	v_fmamk_f32 v14, v102, 0x3e38aa3b, v72
	v_max3_f32 v12, v12, v64, v66
	v_add_f32_e32 v72, v57, v14
	s_waitcnt lgkmcnt(0)
	v_fmamk_f32 v14, v103, 0x3e38aa3b, v74
	v_max3_f32 v12, v12, v68, v70
	v_add_f32_e32 v74, v59, v14
	v_fmac_f32_e32 v13, 0x3e38aa3b, v24
	v_fmac_f32_e32 v15, 0x3e38aa3b, v25
	v_max3_f32 v12, v12, v72, v74
	v_add_f32_e32 v98, v45, v13
	v_add_f32_e32 v99, v47, v15
	v_fmac_f32_e32 v65, 0x3e38aa3b, v26
	v_fmac_f32_e32 v67, 0x3e38aa3b, v27
	v_max3_f32 v12, v12, v98, v99
	v_add_f32_e32 v26, v49, v65
	v_add_f32_e32 v27, v51, v67
	v_fmac_f32_e32 v69, 0x3e38aa3b, v20
	v_fmac_f32_e32 v71, 0x3e38aa3b, v21
	v_max3_f32 v12, v12, v26, v27
	v_add_f32_e32 v65, v53, v69
	v_add_f32_e32 v67, v55, v71
	v_max3_f32 v20, v12, v65, v67
	ds_read2_b32 v[12:13], v63 offset0:162 offset1:193
	ds_read2_b32 v[14:15], v79 offset0:162 offset1:193
	v_fmac_f32_e32 v73, 0x3e38aa3b, v22
	v_fmac_f32_e32 v75, 0x3e38aa3b, v23
	v_add_f32_e32 v69, v57, v73
	v_add_f32_e32 v63, v59, v75
	v_max3_f32 v22, v20, v69, v63
	ds_read2_b32 v[20:21], v81 offset0:162 offset1:193
	s_waitcnt lgkmcnt(2)
	v_fmamk_f32 v12, v16, 0x3e38aa3b, v12
	s_waitcnt lgkmcnt(1)
	v_fmamk_f32 v14, v17, 0x3e38aa3b, v14
	ds_read2_b32 v[16:17], v106 offset0:162 offset1:193
	v_add_f32_e32 v12, v45, v12
	v_add_f32_e32 v71, v47, v14
	v_max3_f32 v14, v22, v12, v71
	s_waitcnt lgkmcnt(1)
	v_fmamk_f32 v18, v18, 0x3e38aa3b, v20
	ds_read2_b32 v[22:23], v83 offset0:162 offset1:193
	v_add_f32_e32 v73, v49, v18
	s_waitcnt lgkmcnt(1)
	v_fmamk_f32 v16, v19, 0x3e38aa3b, v16
	ds_read2_b32 v[18:19], v111 offset0:162 offset1:193
	v_add_f32_e32 v75, v51, v16
	s_waitcnt lgkmcnt(1)
	v_fmamk_f32 v8, v8, 0x3e38aa3b, v22
	v_add_f32_e32 v79, v53, v8
	ds_read2_b32 v[24:25], v85 offset0:162 offset1:193
	s_waitcnt lgkmcnt(1)
; #define LAS __attribute__((address_space(3)))
; __device__ __forceinline__ unsigned cvt_pk_bf16(float lo, float hi) { unsigned r; asm volatile("v_cvt_pk_bf16_f32 %0, %1, %2" : "=v"(r) : "v"(lo), "v"(hi)); return r; }
; __device__ __forceinline__ void attn_phase(const Params& p, LAS unsigned char* lds) {
;     ...
;         mx = fmaxf(mx, __shfl_xor(mx, 16)); mx = fmaxf(mx, __shfl_xor(mx, 32));
;         float sum = 0.f;
; #pragma unroll
;         for (int i = 0; i < 8; ++i)
; #pragma unroll
;             for (int t = 0; t < 2; ++t)
; #pragma unroll
;                 for (int j = 0; j < 4; ++j) { const float e = __builtin_amdgcn_exp2f(s[i][t][j] - mx); s[i][t][j] = e; sum += e; }
;         sum += __shfl_xor(sum, 16); sum += __shfl_xor(sum, 32);
;         const float inv = 1.0f / sum;
;         f32x4 o[4];
; #pragma unroll
;         for (int nb = 0; nb < 4; ++nb) o[nb] = (f32x4){0.f, 0.f, 0.f, 0.f};
;         const int vc = (kc0 >> 3) + fq;
; #pragma unroll
;         for (int i = 0; i < 8; ++i) {
;             u32x4 pw; pw.x = cvt_pk_bf16(s[i][0][0], s[i][0][1]); pw.y = cvt_pk_bf16(s[i][0][2], s[i][0][3]); pw.z = cvt_pk_bf16(s[i][1][0], s[i][1][1]); pw.w = cvt_pk_bf16(s[i][1][2], s[i][1][3]);
;             const bf16x8 pf = __builtin_bit_cast(bf16x8, pw);
; #pragma unroll
;             for (int nb = 0; nb < 4; ++nb) { const int d = nb * 16 + fr; const bf16x8 va = *(const LAS bf16x8*)(Vs + (j0 + i) * 8192 + d * 128 + ((vc ^ ((d >> 1) & 7)) << 4));
;                 o[nb] = __builtin_amdgcn_mfma_f32_16x16x32_bf16(va, pf, o[nb], 0, 0, 0); } }
	v_fmamk_f32 v16, v9, 0x3e38aa3b, v18
	ds_read2_b32 v[8:9], v115 offset0:162 offset1:193
	v_max3_f32 v14, v14, v73, v75
	v_add_f32_e32 v81, v55, v16
	s_waitcnt lgkmcnt(1)
	v_fmamk_f32 v10, v10, 0x3e38aa3b, v24
	v_max3_f32 v14, v14, v79, v81
	s_waitcnt lgkmcnt(0)
	v_fmamk_f32 v8, v11, 0x3e38aa3b, v8
	v_add_f32_e32 v83, v57, v10
	v_add_f32_e32 v85, v59, v8
	v_fmac_f32_e32 v13, 0x3e38aa3b, v0
	v_fmac_f32_e32 v15, 0x3e38aa3b, v1
	v_max3_f32 v8, v14, v83, v85
	v_add_f32_e32 v100, v45, v13
	v_add_f32_e32 v101, v47, v15
	v_fmac_f32_e32 v21, 0x3e38aa3b, v2
	v_fmac_f32_e32 v17, 0x3e38aa3b, v3
	v_and_b32_e32 v2, 64, v62
	v_max3_f32 v0, v8, v100, v101
	v_add_f32_e32 v102, v49, v21
	v_add_f32_e32 v103, v51, v17
	v_fmac_f32_e32 v23, 0x3e38aa3b, v4
	v_fmac_f32_e32 v19, 0x3e38aa3b, v5
	v_xor_b32_e32 v1, 16, v62
	v_add_u32_e32 v2, 64, v2
	v_max3_f32 v0, v0, v102, v103
	v_add_f32_e32 v106, v53, v23
	v_add_f32_e32 v111, v55, v19
	v_fmac_f32_e32 v25, 0x3e38aa3b, v6
	v_fmac_f32_e32 v9, 0x3e38aa3b, v7
	v_cmp_lt_i32_e32 vcc, v1, v2
	v_max3_f32 v0, v0, v106, v111
	v_add_f32_e32 v115, v57, v25
	v_add_f32_e32 v119, v59, v9
	v_cndmask_b32_e32 v1, v62, v1, vcc
	v_max3_f32 v0, v0, v115, v119
	v_lshlrev_b32_e32 v16, 2, v1
	ds_bpermute_b32 v1, v16, v0
	s_waitcnt lgkmcnt(0)
	v_max_f32_e32 v1, v1, v1
	v_max_f32_e32 v0, v0, v1
	v_xor_b32_e32 v1, 32, v62
	v_cmp_lt_i32_e32 vcc, v1, v2
	s_nop 1
	v_cndmask_b32_e32 v1, v62, v1, vcc
	v_lshlrev_b32_e32 v17, 2, v1
	ds_bpermute_b32 v1, v17, v0
	s_waitcnt lgkmcnt(0)
	v_max_f32_e32 v1, v1, v1
	v_max_f32_e32 v124, v0, v1
	v_sub_f32_e32 v0, v104, v124
	v_exp_f32_e32 v0, v0
	v_sub_f32_e32 v1, v112, v124
	v_exp_f32_e32 v1, v1
	v_sub_f32_e32 v2, v113, v124
	v_exp_f32_e32 v2, v2
	v_sub_f32_e32 v3, v116, v124
	v_exp_f32_e32 v3, v3
	v_sub_f32_e32 v5, v117, v124
	v_add_f32_e32 v4, 0, v0
	v_exp_f32_e32 v5, v5
	v_sub_f32_e32 v6, v120, v124
	v_add_f32_e32 v4, v1, v4
	v_exp_f32_e32 v6, v6
	v_sub_f32_e32 v7, v121, v124
	v_add_f32_e32 v4, v2, v4
	v_exp_f32_e32 v7, v7
	v_sub_f32_e32 v8, v108, v124
	v_add_f32_e32 v4, v3, v4
	v_exp_f32_e32 v8, v8
	v_sub_f32_e32 v9, v105, v124
	v_add_f32_e32 v4, v5, v4
	v_exp_f32_e32 v22, v9
	v_sub_f32_e32 v9, v107, v124
	v_add_f32_e32 v4, v6, v4
	v_exp_f32_e32 v23, v9
	v_sub_f32_e32 v9, v122, v124
	v_add_f32_e32 v4, v7, v4
	v_exp_f32_e32 v24, v9
	v_sub_f32_e32 v9, v123, v124
	v_add_f32_e32 v4, v8, v4
	v_exp_f32_e32 v25, v9
	v_sub_f32_e32 v9, v76, v124
	v_add_f32_e32 v4, v22, v4
	v_exp_f32_e32 v76, v9
	v_sub_f32_e32 v9, v77, v124
	v_add_f32_e32 v4, v23, v4
	v_exp_f32_e32 v77, v9
	v_sub_f32_e32 v9, v78, v124
	v_add_f32_e32 v4, v24, v4
	v_exp_f32_e32 v78, v9
	v_sub_f32_e32 v9, v109, v124
	v_add_f32_e32 v4, v25, v4
	v_exp_f32_e32 v104, v9
	v_sub_f32_e32 v9, v80, v124
	v_add_f32_e32 v4, v76, v4
	v_exp_f32_e32 v80, v9
	v_sub_f32_e32 v9, v110, v124
	v_add_f32_e32 v4, v77, v4
	v_exp_f32_e32 v105, v9
	v_sub_f32_e32 v9, v82, v124
	v_add_f32_e32 v4, v78, v4
	v_exp_f32_e32 v82, v9
	v_sub_f32_e32 v9, v114, v124
	v_add_f32_e32 v4, v104, v4
	v_exp_f32_e32 v107, v9
	v_sub_f32_e32 v9, v84, v124
	v_add_f32_e32 v4, v80, v4
	v_exp_f32_e32 v84, v9
	v_sub_f32_e32 v9, v118, v124
	v_add_f32_e32 v4, v105, v4
	v_exp_f32_e32 v108, v9
	v_sub_f32_e32 v9, v86, v124
	v_add_f32_e32 v4, v82, v4
	v_exp_f32_e32 v86, v9
	v_sub_f32_e32 v9, v87, v124
	v_add_f32_e32 v4, v107, v4
	v_exp_f32_e32 v87, v9
	v_sub_f32_e32 v9, v88, v124
	v_add_f32_e32 v4, v84, v4
	v_exp_f32_e32 v88, v9
	v_sub_f32_e32 v9, v89, v124
	v_add_f32_e32 v4, v108, v4
	v_exp_f32_e32 v89, v9
	v_sub_f32_e32 v9, v90, v124
	v_add_f32_e32 v4, v86, v4
	v_exp_f32_e32 v90, v9
	v_sub_f32_e32 v9, v91, v124
	v_add_f32_e32 v4, v87, v4
	v_exp_f32_e32 v91, v9
	v_sub_f32_e32 v9, v92, v124
	v_add_f32_e32 v4, v88, v4
	v_exp_f32_e32 v92, v9
	v_sub_f32_e32 v9, v93, v124
	v_add_f32_e32 v4, v89, v4
	v_exp_f32_e32 v93, v9
	v_sub_f32_e32 v9, v94, v124
	v_add_f32_e32 v4, v90, v4
	v_exp_f32_e32 v94, v9
	v_sub_f32_e32 v9, v95, v124
	v_add_f32_e32 v4, v91, v4
	v_exp_f32_e32 v95, v9
	v_sub_f32_e32 v9, v96, v124
	v_add_f32_e32 v4, v92, v4
	v_exp_f32_e32 v96, v9
	v_sub_f32_e32 v9, v97, v124
	v_add_f32_e32 v4, v93, v4
	v_exp_f32_e32 v97, v9
	v_sub_f32_e32 v9, v64, v124
	v_add_f32_e32 v4, v94, v4
	v_exp_f32_e32 v109, v9
	v_sub_f32_e32 v9, v66, v124
	v_add_f32_e32 v4, v95, v4
	v_exp_f32_e32 v110, v9
	v_sub_f32_e32 v9, v68, v124
	v_add_f32_e32 v4, v96, v4
	v_exp_f32_e32 v112, v9
	v_sub_f32_e32 v9, v70, v124
	v_add_f32_e32 v4, v97, v4
	v_exp_f32_e32 v113, v9
	v_sub_f32_e32 v9, v72, v124
	v_add_f32_e32 v4, v109, v4
	v_exp_f32_e32 v114, v9
	v_sub_f32_e32 v9, v74, v124
	v_add_f32_e32 v4, v110, v4
	v_exp_f32_e32 v116, v9
	v_sub_f32_e32 v9, v98, v124
	v_add_f32_e32 v4, v112, v4
	v_exp_f32_e32 v98, v9
	v_sub_f32_e32 v9, v99, v124
	v_add_f32_e32 v4, v113, v4
	v_exp_f32_e32 v99, v9
	v_sub_f32_e32 v9, v26, v124
	v_add_f32_e32 v4, v114, v4
	v_exp_f32_e32 v26, v9
	v_sub_f32_e32 v9, v27, v124
	v_add_f32_e32 v4, v116, v4
	v_exp_f32_e32 v27, v9
	v_add_f32_e32 v4, v98, v4
	v_add_f32_e32 v4, v99, v4
	v_add_f32_e32 v4, v26, v4
	v_add_f32_e32 v13, v27, v4
	v_sub_f32_e32 v4, v65, v124
	v_exp_f32_e32 v117, v4
	v_sub_f32_e32 v4, v67, v124
	v_exp_f32_e32 v118, v4
	v_sub_f32_e32 v9, v69, v124
	v_cvt_pk_bf16_f32 v0, v0, v1
	v_cvt_pk_bf16_f32 v1, v2, v3
	v_cvt_pk_bf16_f32 v2, v5, v6
	v_cvt_pk_bf16_f32 v3, v7, v8
	v_exp_f32_e32 v121, v9
	v_sub_f32_e32 v8, v63, v124
	v_exp_f32_e32 v63, v8
	v_add_f32_e32 v13, v117, v13
	v_add_f32_e32 v13, v118, v13
	v_add_u32_e32 v120, s16, v41
	v_add_f32_e32 v13, v121, v13
	v_sub_f32_e32 v18, v12, v124
	ds_read_b128 v[4:7], v120
	ds_read_b128 v[8:11], v120 offset:2048
	v_add_f32_e32 v72, v63, v13
	ds_read_b128 v[12:15], v120 offset:4096
	v_exp_f32_e32 v122, v18
	ds_read_b128 v[18:21], v120 offset:6144
	v_sub_f32_e32 v68, v71, v124
	v_cvt_pk_bf16_f32 v22, v22, v23
	v_cvt_pk_bf16_f32 v23, v24, v25
	v_cvt_pk_bf16_f32 v24, v76, v77
	v_exp_f32_e32 v76, v68
	v_cvt_pk_bf16_f32 v25, v78, v104
	ds_read_b128 v[64:67], v120 offset:8192
	ds_read_b128 v[68:71], v120 offset:10240
	s_waitcnt lgkmcnt(5)
; #define LAS __attribute__((address_space(3)))
; __device__ __forceinline__ unsigned cvt_pk_bf16(float lo, float hi) { unsigned r; asm volatile("v_cvt_pk_bf16_f32 %0, %1, %2" : "=v"(r) : "v"(lo), "v"(hi)); return r; }
; __device__ __forceinline__ void attn_phase(const Params& p, LAS unsigned char* lds) {
;     ...
; #pragma unroll
;         for (int i = 0; i < 8; ++i)
; #pragma unroll
;             for (int t = 0; t < 2; ++t)
; #pragma unroll
;                 for (int j = 0; j < 4; ++j) { const float e = __builtin_amdgcn_exp2f(s[i][t][j] - mx); s[i][t][j] = e; sum += e; }
;         sum += __shfl_xor(sum, 16); sum += __shfl_xor(sum, 32);
;         const float inv = 1.0f / sum;
;         f32x4 o[4];
; #pragma unroll
;         for (int nb = 0; nb < 4; ++nb) o[nb] = (f32x4){0.f, 0.f, 0.f, 0.f};
;         const int vc = (kc0 >> 3) + fq;
; #pragma unroll
;         for (int i = 0; i < 8; ++i) {
;             u32x4 pw; pw.x = cvt_pk_bf16(s[i][0][0], s[i][0][1]); pw.y = cvt_pk_bf16(s[i][0][2], s[i][0][3]); pw.z = cvt_pk_bf16(s[i][1][0], s[i][1][1]); pw.w = cvt_pk_bf16(s[i][1][2], s[i][1][3]);
;             const bf16x8 pf = __builtin_bit_cast(bf16x8, pw);
; #pragma unroll
;             for (int nb = 0; nb < 4; ++nb) { const int d = nb * 16 + fr; const bf16x8 va = *(const LAS bf16x8*)(Vs + (j0 + i) * 8192 + d * 128 + ((vc ^ ((d >> 1) & 7)) << 4));
;                 o[nb] = __builtin_amdgcn_mfma_f32_16x16x32_bf16(va, pf, o[nb], 0, 0, 0); } }
	v_mfma_f32_16x16x32_bf16 v[4:7], v[4:7], v[0:3], 0
	v_sub_f32_e32 v104, v75, v124
	s_lshl_b32 s16, s43, 11
	s_add_i32 s44, s44, s16
	s_waitcnt lgkmcnt(4)
	v_mfma_f32_16x16x32_bf16 v[8:11], v[8:11], v[0:3], 0
	s_waitcnt lgkmcnt(3)
	v_mfma_f32_16x16x32_bf16 v[12:15], v[12:15], v[0:3], 0
	s_waitcnt lgkmcnt(2)
	v_mfma_f32_16x16x32_bf16 v[0:3], v[18:21], v[0:3], 0
	v_add_f32_e32 v18, v122, v72
	v_add_f32_e32 v77, v76, v18
	v_sub_f32_e32 v18, v73, v124
	v_exp_f32_e32 v78, v18
	ds_read_b128 v[18:21], v120 offset:12288
	s_waitcnt lgkmcnt(2)
	v_mfma_f32_16x16x32_bf16 v[4:7], v[64:67], v[22:25], v[4:7]
	ds_read_b128 v[64:67], v120 offset:14336
	v_add_f32_e32 v77, v78, v77
	s_waitcnt lgkmcnt(2)
	v_mfma_f32_16x16x32_bf16 v[8:11], v[68:71], v[22:25], v[8:11]
	v_cvt_pk_bf16_f32 v68, v80, v105
	v_cvt_pk_bf16_f32 v69, v82, v107
	v_cvt_pk_bf16_f32 v70, v84, v108
	v_cvt_pk_bf16_f32 v71, v86, v87
	ds_read_b128 v[72:75], v120 offset:16384
	s_waitcnt lgkmcnt(2)
	v_mfma_f32_16x16x32_bf16 v[12:15], v[18:21], v[22:25], v[12:15]
	ds_read_b128 v[18:21], v120 offset:18432
	v_exp_f32_e32 v80, v104
	v_sub_f32_e32 v86, v102, v124
	s_waitcnt lgkmcnt(2)
	v_mfma_f32_16x16x32_bf16 v[0:3], v[64:67], v[22:25], v[0:3]
	v_sub_f32_e32 v22, v79, v124
	v_exp_f32_e32 v79, v22
	ds_read_b128 v[22:25], v120 offset:20480
	s_waitcnt lgkmcnt(1)
	v_mfma_f32_16x16x32_bf16 v[8:11], v[18:21], v[68:71], v[8:11]
	ds_read_b128 v[18:21], v120 offset:22528
	v_sub_f32_e32 v64, v81, v124
	v_exp_f32_e32 v81, v64
	s_waitcnt lgkmcnt(1)
	v_mfma_f32_16x16x32_bf16 v[12:15], v[22:25], v[68:71], v[12:15]
	v_sub_f32_e32 v22, v83, v124
	v_exp_f32_e32 v82, v22
	v_add_f32_e32 v77, v80, v77
	s_waitcnt lgkmcnt(0)
	v_mfma_f32_16x16x32_bf16 v[0:3], v[18:21], v[68:71], v[0:3]
	v_add_f32_e32 v18, v79, v77
	v_cvt_pk_bf16_f32 v64, v88, v89
	v_cvt_pk_bf16_f32 v65, v90, v91
	v_mfma_f32_16x16x32_bf16 v[4:7], v[72:75], v[68:71], v[4:7]
	v_cvt_pk_bf16_f32 v66, v92, v93
	v_cvt_pk_bf16_f32 v67, v94, v95
	ds_read_b128 v[72:75], v120 offset:24576
	ds_read_b128 v[22:25], v120 offset:26624
	v_add_f32_e32 v18, v81, v18
	v_add_f32_e32 v77, v82, v18
	ds_read_b128 v[18:21], v120 offset:28672
	s_waitcnt lgkmcnt(1)
	v_mfma_f32_16x16x32_bf16 v[8:11], v[22:25], v[64:67], v[8:11]
	ds_read_b128 v[22:25], v120 offset:30720
	v_sub_f32_e32 v68, v85, v124
	v_exp_f32_e32 v83, v68
	s_waitcnt lgkmcnt(1)
	v_mfma_f32_16x16x32_bf16 v[12:15], v[18:21], v[64:67], v[12:15]
	v_sub_f32_e32 v18, v100, v124
	v_cvt_pk_bf16_f32 v68, v96, v97
	v_cvt_pk_bf16_f32 v69, v109, v110
	v_mfma_f32_16x16x32_bf16 v[4:7], v[72:75], v[64:67], v[4:7]
	v_cvt_pk_bf16_f32 v70, v112, v113
	v_cvt_pk_bf16_f32 v71, v114, v116
	ds_read_b128 v[72:75], v120 offset:32768
	v_exp_f32_e32 v84, v18
	ds_read_b128 v[18:21], v120 offset:34816
	s_waitcnt lgkmcnt(2)
	v_mfma_f32_16x16x32_bf16 v[0:3], v[22:25], v[64:67], v[0:3]
	v_add_f32_e32 v22, v83, v77
	v_add_f32_e32 v77, v84, v22
	v_sub_f32_e32 v22, v101, v124
	v_exp_f32_e32 v85, v22
	ds_read_b128 v[22:25], v120 offset:36864
	s_waitcnt lgkmcnt(1)
	v_mfma_f32_16x16x32_bf16 v[8:11], v[18:21], v[68:71], v[8:11]
	ds_read_b128 v[18:21], v120 offset:38912
	v_cvt_pk_bf16_f32 v64, v98, v99
	v_cvt_pk_bf16_f32 v65, v26, v27
	v_exp_f32_e32 v26, v86
	v_sub_f32_e32 v27, v103, v124
	v_exp_f32_e32 v27, v27
	s_waitcnt lgkmcnt(0)
	v_mfma_f32_16x16x32_bf16 v[0:3], v[18:21], v[68:71], v[0:3]
	v_add_f32_e32 v18, v85, v77
	v_add_f32_e32 v18, v26, v18
	v_cvt_pk_bf16_f32 v66, v117, v118
	v_mfma_f32_16x16x32_bf16 v[4:7], v[72:75], v[68:71], v[4:7]
	v_cvt_pk_bf16_f32 v67, v121, v63
	ds_read_b128 v[72:75], v120 offset:40960
	v_add_f32_e32 v63, v27, v18
	v_mfma_f32_16x16x32_bf16 v[12:15], v[22:25], v[68:71], v[12:15]
	ds_read_b128 v[22:25], v120 offset:43008
	ds_read_b128 v[18:21], v120 offset:45056
	v_sub_f32_e32 v77, v106, v124
	s_waitcnt lgkmcnt(2)
	v_mfma_f32_16x16x32_bf16 v[4:7], v[72:75], v[64:67], v[4:7]
	s_waitcnt lgkmcnt(1)
; #define LAS __attribute__((address_space(3)))
; __device__ __forceinline__ unsigned cvt_pk_bf16(float lo, float hi) { unsigned r; asm volatile("v_cvt_pk_bf16_f32 %0, %1, %2" : "=v"(r) : "v"(lo), "v"(hi)); return r; }
; __device__ __forceinline__ void attn_phase(const Params& p, LAS unsigned char* lds) {
;     ...
;         for (int i = 0; i < 8; ++i) {
;             u32x4 pw; pw.x = cvt_pk_bf16(s[i][0][0], s[i][0][1]); pw.y = cvt_pk_bf16(s[i][0][2], s[i][0][3]); pw.z = cvt_pk_bf16(s[i][1][0], s[i][1][1]); pw.w = cvt_pk_bf16(s[i][1][2], s[i][1][3]);
;             const bf16x8 pf = __builtin_bit_cast(bf16x8, pw);
; #pragma unroll
;             for (int nb = 0; nb < 4; ++nb) { const int d = nb * 16 + fr; const bf16x8 va = *(const LAS bf16x8*)(Vs + (j0 + i) * 8192 + d * 128 + ((vc ^ ((d >> 1) & 7)) << 4));
;                 o[nb] = __builtin_amdgcn_mfma_f32_16x16x32_bf16(va, pf, o[nb], 0, 0, 0); } }
;         float q2 = 0.f;
; #pragma unroll
;         for (int nb = 0; nb < 4; ++nb) { o[nb] = o[nb] * inv; q2 += (o[nb][0] * o[nb][0] + o[nb][1] * o[nb][1]) + (o[nb][2] * o[nb][2] + o[nb][3] * o[nb][3]); }
;         q2 += __shfl_xor(q2, 16); q2 += __shfl_xor(q2, 32);
;         if (fq == 0) SSQNA[(size_t)tq * 8 + h] = q2;
	v_mfma_f32_16x16x32_bf16 v[8:11], v[22:25], v[64:67], v[8:11]
	ds_read_b128 v[22:25], v120 offset:47104
	v_cvt_pk_bf16_f32 v68, v122, v76
	v_cvt_pk_bf16_f32 v69, v78, v80
	v_cvt_pk_bf16_f32 v70, v79, v81
	v_cvt_pk_bf16_f32 v71, v82, v83
	ds_read_b128 v[72:75], v120 offset:49152
	s_waitcnt lgkmcnt(2)
	v_mfma_f32_16x16x32_bf16 v[12:15], v[18:21], v[64:67], v[12:15]
	ds_read_b128 v[18:21], v120 offset:51200
	v_exp_f32_e32 v76, v77
	v_sub_f32_e32 v77, v111, v124
	s_waitcnt lgkmcnt(2)
	v_mfma_f32_16x16x32_bf16 v[0:3], v[22:25], v[64:67], v[0:3]
	ds_read_b128 v[22:25], v120 offset:53248
	v_exp_f32_e32 v64, v77
	v_sub_f32_e32 v65, v115, v124
	s_waitcnt lgkmcnt(1)
	v_mfma_f32_16x16x32_bf16 v[8:11], v[18:21], v[68:71], v[8:11]
	v_sub_f32_e32 v18, v119, v124
	v_add_f32_e32 v63, v76, v63
	v_add_f32_e32 v63, v64, v63
	v_mfma_f32_16x16x32_bf16 v[4:7], v[72:75], v[68:71], v[4:7]
	v_exp_f32_e32 v73, v18
	ds_read_b128 v[18:21], v120 offset:55296
	v_exp_f32_e32 v72, v65
	s_waitcnt lgkmcnt(1)
	v_mfma_f32_16x16x32_bf16 v[12:15], v[22:25], v[68:71], v[12:15]
	v_cvt_pk_bf16_f32 v22, v84, v85
	v_cvt_pk_bf16_f32 v23, v26, v27
	v_add_f32_e32 v26, v72, v63
	v_cvt_pk_bf16_f32 v24, v76, v64
	v_cvt_pk_bf16_f32 v25, v72, v73
	ds_read_b128 v[64:67], v120 offset:57344
	v_add_f32_e32 v26, v73, v26
	s_waitcnt lgkmcnt(1)
	v_mfma_f32_16x16x32_bf16 v[0:3], v[18:21], v[68:71], v[0:3]
	ds_read_b128 v[18:21], v120 offset:59392
	ds_bpermute_b32 v27, v16, v26
	ds_read_b128 v[68:71], v120 offset:61440
	s_waitcnt lgkmcnt(2)
	v_mfma_f32_16x16x32_bf16 v[18:21], v[18:21], v[22:25], v[8:11]
	s_waitcnt lgkmcnt(1)
	v_add_f32_e32 v26, v26, v27
	ds_bpermute_b32 v27, v17, v26
	ds_read_b128 v[8:11], v120 offset:63488
	v_mfma_f32_16x16x32_bf16 v[4:7], v[64:67], v[22:25], v[4:7]
	s_waitcnt lgkmcnt(1)
	v_add_f32_e32 v26, v26, v27
	v_div_scale_f32 v27, s[20:21], v26, v26, 1.0
	v_rcp_f32_e32 v63, v27
	v_mfma_f32_16x16x32_bf16 v[12:15], v[68:71], v[22:25], v[12:15]
	s_waitcnt lgkmcnt(0)
	v_mfma_f32_16x16x32_bf16 v[22:25], v[8:11], v[22:25], v[0:3]
	s_nop 2
	v_fma_f32 v0, -v27, v63, 1.0
	v_fmac_f32_e32 v63, v0, v63
	v_div_scale_f32 v0, vcc, 1.0, v26, 1.0
	v_mul_f32_e32 v1, v0, v63
	v_fma_f32 v2, -v27, v1, v0
	v_fmac_f32_e32 v1, v2, v63
	v_fma_f32 v0, -v27, v1, v0
	v_div_fmas_f32 v0, v0, v63, v1
	v_div_fixup_f32 v26, v0, v26, 1.0
	v_pk_mul_f32 v[2:3], v[26:27], v[6:7] op_sel_hi:[0,1]
	v_pk_mul_f32 v[10:11], v[26:27], v[4:5] op_sel_hi:[0,1]
	v_mul_f32_e32 v0, v11, v11
	v_mul_f32_e32 v1, v3, v3
	v_fmac_f32_e32 v0, v10, v10
	v_fmac_f32_e32 v1, v2, v2
	v_add_f32_e32 v4, v0, v1
	v_pk_mul_f32 v[0:1], v[26:27], v[20:21] op_sel_hi:[0,1]
	v_pk_mul_f32 v[6:7], v[26:27], v[18:19] op_sel_hi:[0,1]
	v_mul_f32_e32 v5, v7, v7
	v_mul_f32_e32 v8, v1, v1
	v_fmac_f32_e32 v5, v6, v6
	v_fmac_f32_e32 v8, v0, v0
	v_add_f32_e32 v5, v5, v8
	v_add_f32_e32 v8, v4, v5
	v_pk_mul_f32 v[4:5], v[26:27], v[14:15] op_sel_hi:[0,1]
	v_pk_mul_f32 v[12:13], v[26:27], v[12:13] op_sel_hi:[0,1]
	v_mul_f32_e32 v9, v13, v13
	v_mul_f32_e32 v14, v5, v5
	v_fmac_f32_e32 v9, v12, v12
	v_fmac_f32_e32 v14, v4, v4
	v_add_f32_e32 v9, v9, v14
	v_add_f32_e32 v18, v8, v9
	v_pk_mul_f32 v[8:9], v[26:27], v[24:25] op_sel_hi:[0,1]
	v_pk_mul_f32 v[14:15], v[26:27], v[22:23] op_sel_hi:[0,1]
	v_mul_f32_e32 v19, v15, v15
	v_mul_f32_e32 v20, v9, v9
	v_fmac_f32_e32 v19, v14, v14
	v_fmac_f32_e32 v20, v8, v8
	v_add_f32_e32 v19, v19, v20
	v_add_f32_e32 v18, v18, v19
	ds_bpermute_b32 v16, v16, v18
	s_waitcnt lgkmcnt(0)
	v_add_f32_e32 v18, v18, v16
	ds_bpermute_b32 v19, v17, v18
	v_or_b32_e32 v16, s44, v28
	v_ashrrev_i32_e32 v17, 31, v16
	s_and_saveexec_b64 s[20:21], s[4:5]
	s_cbranch_execz .LBB0_336
	s_waitcnt lgkmcnt(0)
	v_add_f32_e32 v20, v18, v19
	v_lshlrev_b64 v[18:19], 5, v[16:17]
	v_lshl_add_u64 v[18:19], s[12:13], 0, v[18:19]
	s_lshl_b32 s16, s42, 2
	v_lshl_add_u64 v[18:19], v[18:19], 0, s[16:17]
	global_store_dword v[18:19], v20, off
	s_branch .LBB0_336
